# w_in/w_out bf16 copies of layers 1..3 deferred from P0b to the scan phase of the previous layer (idle non-scan workgroups), hand-written LDS-DMA copy loop
# speedup vs baseline: 1.0176x; 1.0176x over previous
; #define LAS __attribute__((address_space(3)))
; __device__ __forceinline__ void transpose_item(const float* W, int K, int N, bf16_t* WT, LAS float* scr, int item, int lane) {
;     const int nblk = (N + 31) / 32, kb = item / nblk, nb = item % nblk, k0 = 64 * kb, n0 = 32 * nb;
;     const int nn = n0 + (lane & 31); const bool ok = nn < N;
;     float v[32];
; #pragma unroll
;     for (int i = 0; i < 32; ++i) { const int kk = 2 * i + (lane >> 5); v[i] = ok ? W[(size_t)(k0 + kk) * N + nn] : 0.f; }
; #pragma unroll
;     for (int i = 0; i < 32; ++i) { const int kk = 2 * i + (lane >> 5); scr[kk * 33 + (lane & 31)] = v[i]; }
; __global__ void __launch_bounds__(512, 2) mega(Args a) {
;     ...
;         LAS float* scr = (LAS float*)(lds + wave * 16384);
;         const int it0 = bx < NGEMM ? N1 + bx * 8 + wave : (bx - NGEMM) * 8 + wave, itN = bx < NGEMM ? NIT2 : N1, its = bx < NGEMM ? NGEMM * 8 : (G - NGEMM) * 8;
; #pragma unroll 1
;         for (int it = it0; it < itN; it += its) {
;             int r = it;
;             if (r < 4 * I_IN) { const int l = r / I_IN; r -= l * I_IN; transpose_item(((const float*)ap->in[10]) + (size_t)l * DM * DIN, DM, DIN, WSP(bf16_t, WS_WIN) + (size_t)l * DINP * DM, scr, r, lane); }
;             else { r -= 4 * I_IN; const int l = r / I_OUT; r -= l * I_OUT; transpose_item(((const float*)ap->in[16]) + (size_t)l * DM * DM, DM, DM, WSP(bf16_t, WS_WOUT) + (size_t)l * DM * DM, scr, r, lane); }
;         }
.LBB0_148:
	s_movk_i32 s4, 0xfd00
	s_mov_b32 s14, 0x2820
	s_movk_i32 s15, 0x500
	s_branch .LBB0_150
.LBB0_149:
	s_waitcnt vmcnt(0)
	s_mov_b32 s4, 0x88b8
	s_mov_b32 s14, 0
	s_movk_i32 s15, 0x300
	s_barrier
.LBB0_150:
	s_ashr_i32 s5, s33, 6
	s_lshl_b32 s8, s13, 3
	s_add_i32 s8, s5, s8
	s_add_i32 s13, s8, s4
	s_cmp_ge_i32 s13, s14
	s_cbranch_scc1 .LBB0_221
	s_load_dwordx2 s[16:17], s[0:1], 0x50
	s_load_dwordx2 s[18:19], s[0:1], 0x80
	s_lshl_b32 s10, s5, 14
	s_mov_b32 s42, 0
	s_movk_i32 s43, 0x6060
	v_and_b32_e32 v18, 63, v162
	v_and_b32_e32 v19, 31, v18
	v_lshrrev_b32_e32 v20, 5, v18
	v_xor_b32_e32 v2, 0, v19
	v_lshlrev_b32_e32 v2, 2, v2
	v_xor_b32_e32 v3, 8, v19
	v_lshlrev_b32_e32 v3, 2, v3
	v_xor_b32_e32 v4, 16, v19
	v_lshlrev_b32_e32 v4, 2, v4
	v_xor_b32_e32 v5, 24, v19
	v_lshlrev_b32_e32 v5, 2, v5
	v_mov_b32_e32 v0, v20
	v_and_b32_e32 v19, 7, v18
	v_lshrrev_b32_e32 v20, 3, v18
	v_and_b32_e32 v21, 3, v19
	v_lshlrev_b32_e32 v22, 10, v19
	v_lshl_add_u32 v22, s5, 14, v22
	v_xor_b32_e32 v23, 0, v21
	v_lshl_add_u32 v23, v23, 3, v20
	v_lshl_add_u32 v8, v23, 2, v22
	v_xor_b32_e32 v23, 1, v21
	v_lshl_add_u32 v23, v23, 3, v20
	v_lshl_add_u32 v9, v23, 2, v22
	v_xor_b32_e32 v23, 2, v21
	v_lshl_add_u32 v23, v23, 3, v20
	v_lshl_add_u32 v10, v23, 2, v22
	v_xor_b32_e32 v23, 3, v21
	v_lshl_add_u32 v23, v23, 3, v20
	v_lshl_add_u32 v11, v23, 2, v22
	v_lshlrev_b32_e32 v23, 12, v20
	v_lshl_add_u32 v13, v19, 4, v23
	v_add_u32_e32 v14, 0x8000, v13
	v_add_u32_e32 v15, 0x10000, v13
	v_add_u32_e32 v16, 0x18000, v13
	s_mov_b32 s8, s13
	s_waitcnt vmcnt(0) lgkmcnt(0)
	v_readfirstlane_b32 s20, v128
	v_readfirstlane_b32 s21, v129
	s_mov_b32 s11, s8
	s_cmp_ge_u32 s11, 0x2020
	s_cselect_b32 s36, s43, s42
	s_add_u32 s11, s11, s36
	s_cmp_ge_u32 s11, 0x8080
	s_cbranch_scc1 .Lp0b_la_p0_out
	s_mul_hi_u32 s34, s11, 0x7f808
	s_mul_i32 s36, s34, 0x2020
	s_sub_u32 s11, s11, s36
	s_mul_hi_u32 s35, s11, 0xff0100
	s_mul_i32 s36, s35, 0x101
	s_sub_u32 s11, s11, s36
	s_mul_i32 s36, s34, 0x4020000
	s_mul_i32 s37, s35, 0x201000
	s_add_u32 s36, s36, s37
	s_lshl_b32 s37, s11, 7
	s_add_u32 s36, s36, s37
	s_add_u32 s22, s16, s36
	s_addc_u32 s23, s17, 0
	s_mov_b32 s26, 0x8040
	s_mov_b32 s27, 0x10080
	s_mov_b64 s[28:29], -1
	s_mov_b64 s[30:31], -1
	s_cmp_eq_u32 s11, 0x100
	s_cbranch_scc0 .Lp0b_la_p0_done
	s_mov_b32 s28, 0xffff
	s_mov_b32 s29, 0xffff
	s_mov_b32 s30, 0xffff0000
	s_mov_b32 s31, 0xffff0000
	s_branch .Lp0b_la_p0_done

; #define LAS __attribute__((address_space(3)))
; __device__ __forceinline__ void transpose_item(const float* W, int K, int N, bf16_t* WT, LAS float* scr, int item, int lane) {
;     const int nblk = (N + 31) / 32, kb = item / nblk, nb = item % nblk, k0 = 64 * kb, n0 = 32 * nb;
;     const int nn = n0 + (lane & 31); const bool ok = nn < N;
;     float v[32];
; #pragma unroll
;     for (int i = 0; i < 32; ++i) { const int kk = 2 * i + (lane >> 5); v[i] = ok ? W[(size_t)(k0 + kk) * N + nn] : 0.f; }
; #pragma unroll
;     for (int i = 0; i < 32; ++i) { const int kk = 2 * i + (lane >> 5); scr[kk * 33 + (lane & 31)] = v[i]; }
; __global__ void __launch_bounds__(512, 2) mega(Args a) {
;     ...
; #pragma unroll 1
;         for (int it = it0; it < itN; it += its) {
;             int r = it;
;             if (r < 4 * I_IN) { const int l = r / I_IN; r -= l * I_IN; transpose_item(((const float*)ap->in[10]) + (size_t)l * DM * DIN, DM, DIN, WSP(bf16_t, WS_WIN) + (size_t)l * DINP * DM, scr, r, lane); }
;             else { r -= 4 * I_IN; const int l = r / I_OUT; r -= l * I_OUT; transpose_item(((const float*)ap->in[16]) + (size_t)l * DM * DM, DM, DM, WSP(bf16_t, WS_WOUT) + (size_t)l * DM * DM, scr, r, lane); }
.Lp0b_la_p0_done:
	v_mad_u32_u24 v58, v0, s26, v2
	v_mad_u32_u24 v59, v0, s26, v3
	v_mad_u32_u24 v60, v0, s26, v4
	v_mad_u32_u24 v61, v0, s26, v5
	s_mov_b64 exec, s[28:29]
	s_mov_b32 m0, s10
	s_nop 0
	global_load_lds_dword v58, s[22:23]
	s_add_i32 m0, m0, 0x100
	s_add_u32 s22, s22, s27
	s_addc_u32 s23, s23, 0
	global_load_lds_dword v58, s[22:23]
	s_add_i32 m0, m0, 0x100
	s_add_u32 s22, s22, s27
	s_addc_u32 s23, s23, 0
	global_load_lds_dword v58, s[22:23]
	s_add_i32 m0, m0, 0x100
	s_add_u32 s22, s22, s27
	s_addc_u32 s23, s23, 0
	global_load_lds_dword v58, s[22:23]
	s_mov_b64 exec, s[28:29]
	s_add_i32 m0, m0, 0x100
	s_add_u32 s22, s22, s27
	s_addc_u32 s23, s23, 0
	global_load_lds_dword v59, s[22:23]
	s_add_i32 m0, m0, 0x100
	s_add_u32 s22, s22, s27
	s_addc_u32 s23, s23, 0
	global_load_lds_dword v59, s[22:23]
	s_add_i32 m0, m0, 0x100
	s_add_u32 s22, s22, s27
	s_addc_u32 s23, s23, 0
	global_load_lds_dword v59, s[22:23]
	s_add_i32 m0, m0, 0x100
	s_add_u32 s22, s22, s27
	s_addc_u32 s23, s23, 0
	global_load_lds_dword v59, s[22:23]
	s_mov_b64 exec, s[30:31]
	s_add_i32 m0, m0, 0x100
	s_add_u32 s22, s22, s27
	s_addc_u32 s23, s23, 0
	global_load_lds_dword v60, s[22:23]
	s_add_i32 m0, m0, 0x100
	s_add_u32 s22, s22, s27
	s_addc_u32 s23, s23, 0
	global_load_lds_dword v60, s[22:23]
	s_add_i32 m0, m0, 0x100
	s_add_u32 s22, s22, s27
	s_addc_u32 s23, s23, 0
	global_load_lds_dword v60, s[22:23]
	s_add_i32 m0, m0, 0x100
	s_add_u32 s22, s22, s27
	s_addc_u32 s23, s23, 0
	global_load_lds_dword v60, s[22:23]
	s_mov_b64 exec, s[30:31]
	s_add_i32 m0, m0, 0x100
	s_add_u32 s22, s22, s27
	s_addc_u32 s23, s23, 0
	global_load_lds_dword v61, s[22:23]
	s_add_i32 m0, m0, 0x100
	s_add_u32 s22, s22, s27
	s_addc_u32 s23, s23, 0
	global_load_lds_dword v61, s[22:23]
	s_add_i32 m0, m0, 0x100
	s_add_u32 s22, s22, s27
	s_addc_u32 s23, s23, 0
	global_load_lds_dword v61, s[22:23]
	s_add_i32 m0, m0, 0x100
	s_add_u32 s22, s22, s27
	s_addc_u32 s23, s23, 0
	global_load_lds_dword v61, s[22:23]
	s_mov_b64 exec, s[28:29]
	s_add_i32 m0, m0, 0x100
	s_add_u32 s22, s22, s27
	s_addc_u32 s23, s23, 0
	global_load_lds_dword v58, s[22:23]
	s_add_i32 m0, m0, 0x100
	s_add_u32 s22, s22, s27
	s_addc_u32 s23, s23, 0
	global_load_lds_dword v58, s[22:23]
	s_add_i32 m0, m0, 0x100
	s_add_u32 s22, s22, s27
	s_addc_u32 s23, s23, 0
	global_load_lds_dword v58, s[22:23]
	s_add_i32 m0, m0, 0x100
	s_add_u32 s22, s22, s27
	s_addc_u32 s23, s23, 0
	global_load_lds_dword v58, s[22:23]
	s_mov_b64 exec, s[28:29]
	s_add_i32 m0, m0, 0x100
	s_add_u32 s22, s22, s27
	s_addc_u32 s23, s23, 0
	global_load_lds_dword v59, s[22:23]
	s_add_i32 m0, m0, 0x100
	s_add_u32 s22, s22, s27
	s_addc_u32 s23, s23, 0
	global_load_lds_dword v59, s[22:23]
	s_add_i32 m0, m0, 0x100
	s_add_u32 s22, s22, s27
	s_addc_u32 s23, s23, 0
	global_load_lds_dword v59, s[22:23]
	s_add_i32 m0, m0, 0x100
	s_add_u32 s22, s22, s27
	s_addc_u32 s23, s23, 0
	global_load_lds_dword v59, s[22:23]
	s_mov_b64 exec, s[30:31]
	s_add_i32 m0, m0, 0x100
	s_add_u32 s22, s22, s27
	s_addc_u32 s23, s23, 0
	global_load_lds_dword v60, s[22:23]
	s_add_i32 m0, m0, 0x100
	s_add_u32 s22, s22, s27
	s_addc_u32 s23, s23, 0
	global_load_lds_dword v60, s[22:23]
	s_add_i32 m0, m0, 0x100
	s_add_u32 s22, s22, s27
	s_addc_u32 s23, s23, 0
	global_load_lds_dword v60, s[22:23]
	s_add_i32 m0, m0, 0x100
	s_add_u32 s22, s22, s27
	s_addc_u32 s23, s23, 0
	global_load_lds_dword v60, s[22:23]
	s_mov_b64 exec, s[30:31]
	s_add_i32 m0, m0, 0x100
	s_add_u32 s22, s22, s27
	s_addc_u32 s23, s23, 0
	global_load_lds_dword v61, s[22:23]
	s_add_i32 m0, m0, 0x100
	s_add_u32 s22, s22, s27
	s_addc_u32 s23, s23, 0
	global_load_lds_dword v61, s[22:23]
	s_add_i32 m0, m0, 0x100
	s_add_u32 s22, s22, s27
	s_addc_u32 s23, s23, 0
	global_load_lds_dword v61, s[22:23]
	s_add_i32 m0, m0, 0x100
	s_add_u32 s22, s22, s27
	s_addc_u32 s23, s23, 0
	global_load_lds_dword v61, s[22:23]
	s_mov_b64 exec, -1
	s_add_i32 s9, s8, s15
	s_cmp_lt_i32 s9, s14
	s_cbranch_scc0 .Lp0b_nopf1
	s_mov_b32 s11, s9
	s_cmp_ge_u32 s11, 0x2020
	s_cselect_b32 s36, s43, s42
	s_add_u32 s11, s11, s36
	s_cmp_ge_u32 s11, 0x8080
	s_cbranch_scc1 .Lp0b_la_p1_out
	s_mul_hi_u32 s34, s11, 0x7f808
	s_mul_i32 s36, s34, 0x2020
	s_sub_u32 s11, s11, s36
	s_mul_hi_u32 s35, s11, 0xff0100
	s_mul_i32 s36, s35, 0x101
	s_sub_u32 s11, s11, s36
	s_mul_i32 s36, s34, 0x4020000
	s_mul_i32 s37, s35, 0x201000
	s_add_u32 s36, s36, s37
	s_lshl_b32 s37, s11, 7
	s_add_u32 s36, s36, s37
	s_add_u32 s22, s16, s36
	s_addc_u32 s23, s17, 0
	s_mov_b32 s26, 0x8040
	s_mov_b32 s27, 0x10080
	s_mov_b64 s[28:29], -1
	s_mov_b64 s[30:31], -1
	s_cmp_eq_u32 s11, 0x100
	s_cbranch_scc0 .Lp0b_la_p1_done
	s_mov_b32 s28, 0xffff
	s_mov_b32 s29, 0xffff
	s_mov_b32 s30, 0xffff0000
	s_mov_b32 s31, 0xffff0000
	s_branch .Lp0b_la_p1_done

; #define LAS __attribute__((address_space(3)))
; __device__ __forceinline__ unsigned pk2(float lo, float hi) { return pg8::cvt_pk_bf16(lo, hi); }
; #define LDS_WAIT() asm volatile("s_waitcnt lgkmcnt(0)" ::: "memory")
; __device__ __forceinline__ void transpose_item(const float* W, int K, int N, bf16_t* WT, LAS float* scr, int item, int lane) {
;     const int nblk = (N + 31) / 32, kb = item / nblk, nb = item % nblk, k0 = 64 * kb, n0 = 32 * nb;
;     const int nn = n0 + (lane & 31); const bool ok = nn < N;
;     float v[32];
; #pragma unroll
;     for (int i = 0; i < 32; ++i) { const int kk = 2 * i + (lane >> 5); v[i] = ok ? W[(size_t)(k0 + kk) * N + nn] : 0.f; }
; #pragma unroll
;     for (int i = 0; i < 32; ++i) { const int kk = 2 * i + (lane >> 5); scr[kk * 33 + (lane & 31)] = v[i]; }
;     LDS_WAIT(); asm volatile("" ::: "memory");
;     const int c = lane & 7;
; #pragma unroll
;     for (int j = 0; j < 4; ++j) { const int n = (lane >> 3) + 8 * j; const LAS float* s = scr + (8 * c) * 33 + n;
;         u32x4 o; o.x = pk2(s[0 * 33], s[1 * 33]); o.y = pk2(s[2 * 33], s[3 * 33]); o.z = pk2(s[4 * 33], s[5 * 33]); o.w = pk2(s[6 * 33], s[7 * 33]);
;         *(u32x4*)(WT + (size_t)(n0 + n) * K + k0 + 8 * c) = o; }
; __global__ void __launch_bounds__(512, 2) mega(Args a) {
;     ...
; #pragma unroll 1
;         for (int it = it0; it < itN; it += its) {
;             int r = it;
;             if (r < 4 * I_IN) { const int l = r / I_IN; r -= l * I_IN; transpose_item(((const float*)ap->in[10]) + (size_t)l * DM * DIN, DM, DIN, WSP(bf16_t, WS_WIN) + (size_t)l * DINP * DM, scr, r, lane); }
;             else { r -= 4 * I_IN; const int l = r / I_OUT; r -= l * I_OUT; transpose_item(((const float*)ap->in[16]) + (size_t)l * DM * DM, DM, DM, WSP(bf16_t, WS_WOUT) + (size_t)l * DM * DM, scr, r, lane); }
.Lp0b_loop:
	s_mov_b32 s11, s8
	s_mov_b64 s[40:41], 0
	s_cmp_ge_u32 s11, 0x2020
	s_cselect_b32 s36, s43, s42
	s_add_u32 s11, s11, s36
	s_cmp_ge_u32 s11, 0x8080
	s_cbranch_scc1 .Lp0b_sa_out
	s_mul_hi_u32 s34, s11, 0x7f808
	s_mul_i32 s36, s34, 0x2020
	s_sub_u32 s11, s11, s36
	s_mul_hi_u32 s35, s11, 0xff0100
	s_mul_i32 s36, s35, 0x101
	s_sub_u32 s11, s11, s36
	s_mul_i32 s36, s34, 0x2020000
	s_cmp_eq_u32 s11, 0x100
	s_cselect_b32 s40, -1, 0
	s_mov_b32 s41, s40
	s_branch .Lp0b_sa_done

; #define LAS __attribute__((address_space(3)))
; __device__ __forceinline__ unsigned pk2(float lo, float hi) { return pg8::cvt_pk_bf16(lo, hi); }
; #define LDS_WAIT() asm volatile("s_waitcnt lgkmcnt(0)" ::: "memory")
; __device__ __forceinline__ void transpose_item(const float* W, int K, int N, bf16_t* WT, LAS float* scr, int item, int lane) {
;     ...
;     const int c = lane & 7;
; #pragma unroll
;     for (int j = 0; j < 4; ++j) { const int n = (lane >> 3) + 8 * j; const LAS float* s = scr + (8 * c) * 33 + n;
;         u32x4 o; o.x = pk2(s[0 * 33], s[1 * 33]); o.y = pk2(s[2 * 33], s[3 * 33]); o.z = pk2(s[4 * 33], s[5 * 33]); o.w = pk2(s[6 * 33], s[7 * 33]);
;         *(u32x4*)(WT + (size_t)(n0 + n) * K + k0 + 8 * c) = o; }
;     LDS_WAIT(); asm volatile("" ::: "memory");
; }
.Lp0b_wd:
	ds_read2_b32 v[18:19], v8 offset0:0 offset1:32
	ds_read2_b32 v[20:21], v8 offset0:64 offset1:96
	ds_read2_b32 v[22:23], v8 offset0:128 offset1:160
	ds_read2_b32 v[24:25], v8 offset0:192 offset1:224
	ds_read2_b32 v[26:27], v9 offset0:0 offset1:32
	ds_read2_b32 v[28:29], v9 offset0:64 offset1:96
	ds_read2_b32 v[30:31], v9 offset0:128 offset1:160
	ds_read2_b32 v[32:33], v9 offset0:192 offset1:224
	ds_read2_b32 v[34:35], v10 offset0:0 offset1:32
	ds_read2_b32 v[36:37], v10 offset0:64 offset1:96
	ds_read2_b32 v[38:39], v10 offset0:128 offset1:160
	ds_read2_b32 v[40:41], v10 offset0:192 offset1:224
	ds_read2_b32 v[42:43], v11 offset0:0 offset1:32
	ds_read2_b32 v[44:45], v11 offset0:64 offset1:96
	ds_read2_b32 v[46:47], v11 offset0:128 offset1:160
	ds_read2_b32 v[48:49], v11 offset0:192 offset1:224
	s_waitcnt lgkmcnt(12)
	v_cvt_pk_bf16_f32 v50, v18, v19
	v_cvt_pk_bf16_f32 v51, v20, v21
	v_cvt_pk_bf16_f32 v52, v22, v23
	v_cvt_pk_bf16_f32 v53, v24, v25
	global_store_dwordx4 v13, v[50:53], s[24:25]
	s_waitcnt lgkmcnt(8)
	v_cvt_pk_bf16_f32 v54, v26, v27
	v_cvt_pk_bf16_f32 v55, v28, v29
	v_cvt_pk_bf16_f32 v56, v30, v31
	v_cvt_pk_bf16_f32 v57, v32, v33
	global_store_dwordx4 v14, v[54:57], s[24:25]
	s_waitcnt lgkmcnt(4)
	v_cvt_pk_bf16_f32 v50, v34, v35
	v_cvt_pk_bf16_f32 v51, v36, v37
	v_cvt_pk_bf16_f32 v52, v38, v39
	v_cvt_pk_bf16_f32 v53, v40, v41
	v_cndmask_b32_e64 v50, v50, 0, s[40:41]
	v_cndmask_b32_e64 v51, v51, 0, s[40:41]
	v_cndmask_b32_e64 v52, v52, 0, s[40:41]
	v_cndmask_b32_e64 v53, v53, 0, s[40:41]
	global_store_dwordx4 v15, v[50:53], s[24:25]
	s_waitcnt lgkmcnt(0)
	v_cvt_pk_bf16_f32 v54, v42, v43
	v_cvt_pk_bf16_f32 v55, v44, v45
	v_cvt_pk_bf16_f32 v56, v46, v47
	v_cvt_pk_bf16_f32 v57, v48, v49
	v_cndmask_b32_e64 v54, v54, 0, s[40:41]
	v_cndmask_b32_e64 v55, v55, 0, s[40:41]
	v_cndmask_b32_e64 v56, v56, 0, s[40:41]
	v_cndmask_b32_e64 v57, v57, 0, s[40:41]
	global_store_dwordx4 v16, v[54:57], s[24:25]
	s_cmp_lt_i32 s9, s14
	s_cbranch_scc0 .Lp0b_nopf
	s_mov_b32 s11, s9
	s_cmp_ge_u32 s11, 0x2020
	s_cselect_b32 s36, s43, s42
	s_add_u32 s11, s11, s36
	s_cmp_ge_u32 s11, 0x8080
	s_cbranch_scc1 .Lp0b_la_lp_out
	s_mul_hi_u32 s34, s11, 0x7f808
	s_mul_i32 s36, s34, 0x2020
	s_sub_u32 s11, s11, s36
	s_mul_hi_u32 s35, s11, 0xff0100
	s_mul_i32 s36, s35, 0x101
	s_sub_u32 s11, s11, s36
	s_mul_i32 s36, s34, 0x4020000
	s_mul_i32 s37, s35, 0x201000
	s_add_u32 s36, s36, s37
	s_lshl_b32 s37, s11, 7
	s_add_u32 s36, s36, s37
	s_add_u32 s22, s16, s36
	s_addc_u32 s23, s17, 0
	s_mov_b32 s26, 0x8040
	s_mov_b32 s27, 0x10080
	s_mov_b64 s[28:29], -1
	s_mov_b64 s[30:31], -1
	s_cmp_eq_u32 s11, 0x100
	s_cbranch_scc0 .Lp0b_la_lp_done
	s_mov_b32 s28, 0xffff
	s_mov_b32 s29, 0xffff
	s_mov_b32 s30, 0xffff0000
	s_mov_b32 s31, 0xffff0000
	s_branch .Lp0b_la_lp_done

; #define LAS __attribute__((address_space(3)))
; __device__ __forceinline__ void transpose_item(const float* W, int K, int N, bf16_t* WT, LAS float* scr, int item, int lane) {
;     const int nblk = (N + 31) / 32, kb = item / nblk, nb = item % nblk, k0 = 64 * kb, n0 = 32 * nb;
;     const int nn = n0 + (lane & 31); const bool ok = nn < N;
;     float v[32];
; #pragma unroll
;     for (int i = 0; i < 32; ++i) { const int kk = 2 * i + (lane >> 5); v[i] = ok ? W[(size_t)(k0 + kk) * N + nn] : 0.f; }
; #pragma unroll
;     for (int i = 0; i < 32; ++i) { const int kk = 2 * i + (lane >> 5); scr[kk * 33 + (lane & 31)] = v[i]; }
; __global__ void __launch_bounds__(512, 2) mega(Args a) {
;     ...
;         for (int it = it0; it < itN; it += its) {
;             int r = it;
;             if (r < 4 * I_IN) { const int l = r / I_IN; r -= l * I_IN; transpose_item(((const float*)ap->in[10]) + (size_t)l * DM * DIN, DM, DIN, WSP(bf16_t, WS_WIN) + (size_t)l * DINP * DM, scr, r, lane); }
;             else { r -= 4 * I_IN; const int l = r / I_OUT; r -= l * I_OUT; transpose_item(((const float*)ap->in[16]) + (size_t)l * DM * DM, DM, DM, WSP(bf16_t, WS_WOUT) + (size_t)l * DM * DM, scr, r, lane); }
.LBB0_513:
	s_or_b64 exec, exec, s[4:5]
	s_mov_b64 exec, -1
	s_waitcnt vmcnt(0) lgkmcnt(0)
	s_cmp_gt_u32 s92, 2
	s_cbranch_scc1 .Lp4t_skip
	s_load_dwordx2 s[22:23], s[0:1], 0x50
	s_load_dwordx2 s[24:25], s[0:1], 0x80
	s_load_dwordx2 s[26:27], s[0:1], 0x98
	s_lshr_b32 s38, s3, 6
	s_lshl_b32 s6, s38, 14
	v_mbcnt_lo_u32_b32 v24, -1, 0
	v_mbcnt_hi_u32_b32 v24, -1, v24
	v_and_b32_e32 v18, 63, v24
	v_and_b32_e32 v19, 31, v18
	v_lshrrev_b32_e32 v20, 5, v18
	v_xor_b32_e32 v2, 0, v19
	v_lshlrev_b32_e32 v2, 2, v2
	v_xor_b32_e32 v3, 8, v19
	v_lshlrev_b32_e32 v3, 2, v3
	v_xor_b32_e32 v4, 16, v19
	v_lshlrev_b32_e32 v4, 2, v4
	v_xor_b32_e32 v5, 24, v19
	v_lshlrev_b32_e32 v5, 2, v5
	v_mov_b32_e32 v0, v20
	v_and_b32_e32 v19, 7, v18
	v_lshrrev_b32_e32 v20, 3, v18
	v_and_b32_e32 v21, 3, v19
	v_lshlrev_b32_e32 v22, 10, v19
	v_lshl_add_u32 v22, s38, 14, v22
	v_xor_b32_e32 v23, 0, v21
	v_lshl_add_u32 v23, v23, 3, v20
	v_lshl_add_u32 v62, v23, 2, v22
	v_xor_b32_e32 v23, 1, v21
	v_lshl_add_u32 v23, v23, 3, v20
	v_lshl_add_u32 v63, v23, 2, v22
	v_xor_b32_e32 v23, 2, v21
	v_lshl_add_u32 v23, v23, 3, v20
	v_lshl_add_u32 v64, v23, 2, v22
	v_xor_b32_e32 v23, 3, v21
	v_lshl_add_u32 v23, v23, 3, v20
	v_lshl_add_u32 v65, v23, 2, v22
	v_lshlrev_b32_e32 v23, 12, v20
	v_lshl_add_u32 v13, v19, 4, v23
	v_add_u32_e32 v14, 0x8000, v13
	v_add_u32_e32 v15, 0x10000, v13
	v_add_u32_e32 v16, 0x18000, v13
	s_sub_u32 s4, s2, 64
	s_lshl_b32 s4, s4, 3
	s_add_u32 s4, s4, s38
	s_movk_i32 s16, 0x2820
	s_movk_i32 s18, 0x600
	s_add_u32 s70, s92, 1
	s_mul_i32 s98, s70, 0x2020
	s_lshl_b32 s99, s70, 11
	s_addk_i32 s99, 0x6060
	s_waitcnt lgkmcnt(0)
	s_mov_b32 s7, s4
	s_cmp_ge_u32 s7, 0x2020
	s_cselect_b32 s70, s99, s98
	s_add_u32 s7, s7, s70
	s_cmp_ge_u32 s7, 0x8080
	s_cbranch_scc1 .Lp4t_la_p0_out
	s_mul_hi_u32 s38, s7, 0x7f808
	s_mul_i32 s70, s38, 0x2020
	s_sub_u32 s7, s7, s70
	s_mul_hi_u32 s55, s7, 0xff0100
	s_mul_i32 s70, s55, 0x101
	s_sub_u32 s7, s7, s70
	s_mul_i32 s70, s38, 0x4020000
	s_mul_i32 s71, s55, 0x201000
	s_add_u32 s70, s70, s71
	s_lshl_b32 s71, s7, 7
	s_add_u32 s70, s70, s71
	s_add_u32 s28, s22, s70
	s_addc_u32 s29, s23, 0
	s_mov_b32 s19, 0x8040
	s_mov_b32 s32, 0x10080
	s_mov_b64 s[34:35], -1
	s_mov_b64 s[36:37], -1
	s_cmp_eq_u32 s7, 0x100
	s_cbranch_scc0 .Lp4t_la_p0_done
	s_mov_b32 s34, 0xffff
	s_mov_b32 s35, 0xffff
	s_mov_b32 s36, 0xffff0000
	s_mov_b32 s37, 0xffff0000
	s_branch .Lp4t_la_p0_done
.Lp4t_la_p0_out:
	s_sub_u32 s7, s7, 0x8080
	s_lshr_b32 s38, s7, 11
	s_and_b32 s7, s7, 0x7ff
	s_lshr_b32 s55, s7, 6
	s_and_b32 s7, s7, 63
	s_lshl_b32 s70, s38, 24
	s_lshl_b32 s71, s55, 19
	s_add_u32 s70, s70, s71
	s_lshl_b32 s71, s7, 7
	s_add_u32 s70, s70, s71
	s_add_u32 s28, s24, s70
	s_addc_u32 s29, s25, 0
	s_mov_b32 s19, 0x2000
	s_mov_b32 s32, 0x4000
	s_mov_b64 s[34:35], -1
	s_mov_b64 s[36:37], -1
; #define LAS __attribute__((address_space(3)))
; __device__ __forceinline__ void transpose_item(const float* W, int K, int N, bf16_t* WT, LAS float* scr, int item, int lane) {
;     const int nblk = (N + 31) / 32, kb = item / nblk, nb = item % nblk, k0 = 64 * kb, n0 = 32 * nb;
;     const int nn = n0 + (lane & 31); const bool ok = nn < N;
;     float v[32];
; #pragma unroll
;     for (int i = 0; i < 32; ++i) { const int kk = 2 * i + (lane >> 5); v[i] = ok ? W[(size_t)(k0 + kk) * N + nn] : 0.f; }
; #pragma unroll
;     for (int i = 0; i < 32; ++i) { const int kk = 2 * i + (lane >> 5); scr[kk * 33 + (lane & 31)] = v[i]; }
.Lp4t_la_p0_done:
	v_mad_u32_u24 v58, v0, s19, v2
	v_mad_u32_u24 v59, v0, s19, v3
	v_mad_u32_u24 v60, v0, s19, v4
	v_mad_u32_u24 v61, v0, s19, v5
	s_mov_b64 exec, s[34:35]
	s_mov_b32 m0, s6
	s_nop 0
	global_load_lds_dword v58, s[28:29]
	s_add_i32 m0, m0, 0x100
	s_add_u32 s28, s28, s32
	s_addc_u32 s29, s29, 0
	global_load_lds_dword v58, s[28:29]
	s_add_i32 m0, m0, 0x100
	s_add_u32 s28, s28, s32
	s_addc_u32 s29, s29, 0
	global_load_lds_dword v58, s[28:29]
	s_add_i32 m0, m0, 0x100
	s_add_u32 s28, s28, s32
	s_addc_u32 s29, s29, 0
	global_load_lds_dword v58, s[28:29]
	s_mov_b64 exec, s[34:35]
	s_add_i32 m0, m0, 0x100
	s_add_u32 s28, s28, s32
	s_addc_u32 s29, s29, 0
	global_load_lds_dword v59, s[28:29]
	s_add_i32 m0, m0, 0x100
	s_add_u32 s28, s28, s32
	s_addc_u32 s29, s29, 0
	global_load_lds_dword v59, s[28:29]
	s_add_i32 m0, m0, 0x100
	s_add_u32 s28, s28, s32
	s_addc_u32 s29, s29, 0
	global_load_lds_dword v59, s[28:29]
	s_add_i32 m0, m0, 0x100
	s_add_u32 s28, s28, s32
	s_addc_u32 s29, s29, 0
	global_load_lds_dword v59, s[28:29]
	s_mov_b64 exec, s[36:37]
	s_add_i32 m0, m0, 0x100
	s_add_u32 s28, s28, s32
	s_addc_u32 s29, s29, 0
	global_load_lds_dword v60, s[28:29]
	s_add_i32 m0, m0, 0x100
	s_add_u32 s28, s28, s32
	s_addc_u32 s29, s29, 0
	global_load_lds_dword v60, s[28:29]
	s_add_i32 m0, m0, 0x100
	s_add_u32 s28, s28, s32
	s_addc_u32 s29, s29, 0
	global_load_lds_dword v60, s[28:29]
	s_add_i32 m0, m0, 0x100
	s_add_u32 s28, s28, s32
	s_addc_u32 s29, s29, 0
	global_load_lds_dword v60, s[28:29]
	s_mov_b64 exec, s[36:37]
	s_add_i32 m0, m0, 0x100
	s_add_u32 s28, s28, s32
	s_addc_u32 s29, s29, 0
	global_load_lds_dword v61, s[28:29]
	s_add_i32 m0, m0, 0x100
	s_add_u32 s28, s28, s32
	s_addc_u32 s29, s29, 0
	global_load_lds_dword v61, s[28:29]
	s_add_i32 m0, m0, 0x100
	s_add_u32 s28, s28, s32
	s_addc_u32 s29, s29, 0
	global_load_lds_dword v61, s[28:29]
	s_add_i32 m0, m0, 0x100
	s_add_u32 s28, s28, s32
	s_addc_u32 s29, s29, 0
	global_load_lds_dword v61, s[28:29]
	s_mov_b64 exec, s[34:35]
	s_add_i32 m0, m0, 0x100
	s_add_u32 s28, s28, s32
	s_addc_u32 s29, s29, 0
	global_load_lds_dword v58, s[28:29]
	s_add_i32 m0, m0, 0x100
	s_add_u32 s28, s28, s32
	s_addc_u32 s29, s29, 0
	global_load_lds_dword v58, s[28:29]
	s_add_i32 m0, m0, 0x100
	s_add_u32 s28, s28, s32
	s_addc_u32 s29, s29, 0
	global_load_lds_dword v58, s[28:29]
	s_add_i32 m0, m0, 0x100
	s_add_u32 s28, s28, s32
	s_addc_u32 s29, s29, 0
	global_load_lds_dword v58, s[28:29]
	s_mov_b64 exec, s[34:35]
	s_add_i32 m0, m0, 0x100
	s_add_u32 s28, s28, s32
	s_addc_u32 s29, s29, 0
	global_load_lds_dword v59, s[28:29]
	s_add_i32 m0, m0, 0x100
	s_add_u32 s28, s28, s32
	s_addc_u32 s29, s29, 0
	global_load_lds_dword v59, s[28:29]
	s_add_i32 m0, m0, 0x100
	s_add_u32 s28, s28, s32
	s_addc_u32 s29, s29, 0
	global_load_lds_dword v59, s[28:29]
	s_add_i32 m0, m0, 0x100
	s_add_u32 s28, s28, s32
	s_addc_u32 s29, s29, 0
	global_load_lds_dword v59, s[28:29]
	s_mov_b64 exec, s[36:37]
	s_add_i32 m0, m0, 0x100
	s_add_u32 s28, s28, s32
	s_addc_u32 s29, s29, 0
	global_load_lds_dword v60, s[28:29]
	s_add_i32 m0, m0, 0x100
	s_add_u32 s28, s28, s32
	s_addc_u32 s29, s29, 0
	global_load_lds_dword v60, s[28:29]
	s_add_i32 m0, m0, 0x100
	s_add_u32 s28, s28, s32
	s_addc_u32 s29, s29, 0
	global_load_lds_dword v60, s[28:29]
	s_add_i32 m0, m0, 0x100
	s_add_u32 s28, s28, s32
	s_addc_u32 s29, s29, 0
	global_load_lds_dword v60, s[28:29]
	s_mov_b64 exec, s[36:37]
	s_add_i32 m0, m0, 0x100
	s_add_u32 s28, s28, s32
	s_addc_u32 s29, s29, 0
	global_load_lds_dword v61, s[28:29]
	s_add_i32 m0, m0, 0x100
	s_add_u32 s28, s28, s32
	s_addc_u32 s29, s29, 0
	global_load_lds_dword v61, s[28:29]
	s_add_i32 m0, m0, 0x100
	s_add_u32 s28, s28, s32
	s_addc_u32 s29, s29, 0
	global_load_lds_dword v61, s[28:29]
	s_add_i32 m0, m0, 0x100
	s_add_u32 s28, s28, s32
	s_addc_u32 s29, s29, 0
	global_load_lds_dword v61, s[28:29]
	s_mov_b64 exec, -1
	s_add_i32 s5, s4, s18
	s_cmp_lt_i32 s5, s16
	s_cbranch_scc0 .Lp4t_nopf1
	s_mov_b32 s7, s5
	s_cmp_ge_u32 s7, 0x2020
	s_cselect_b32 s70, s99, s98
	s_add_u32 s7, s7, s70
	s_cmp_ge_u32 s7, 0x8080
	s_cbranch_scc1 .Lp4t_la_p1_out
	s_mul_hi_u32 s38, s7, 0x7f808
	s_mul_i32 s70, s38, 0x2020
	s_sub_u32 s7, s7, s70
	s_mul_hi_u32 s55, s7, 0xff0100
	s_mul_i32 s70, s55, 0x101
	s_sub_u32 s7, s7, s70
	s_mul_i32 s70, s38, 0x4020000
	s_mul_i32 s71, s55, 0x201000
	s_add_u32 s70, s70, s71
	s_lshl_b32 s71, s7, 7
	s_add_u32 s70, s70, s71
	s_add_u32 s28, s22, s70
	s_addc_u32 s29, s23, 0
	s_mov_b32 s19, 0x8040
	s_mov_b32 s32, 0x10080
	s_mov_b64 s[34:35], -1
	s_mov_b64 s[36:37], -1
	s_cmp_eq_u32 s7, 0x100
	s_cbranch_scc0 .Lp4t_la_p1_done
	s_mov_b32 s34, 0xffff
	s_mov_b32 s35, 0xffff
	s_mov_b32 s36, 0xffff0000
	s_mov_b32 s37, 0xffff0000
	s_branch .Lp4t_la_p1_done

; #define LAS __attribute__((address_space(3)))
; __device__ __forceinline__ unsigned pk2(float lo, float hi) { return pg8::cvt_pk_bf16(lo, hi); }
; #define LDS_WAIT() asm volatile("s_waitcnt lgkmcnt(0)" ::: "memory")
; __device__ __forceinline__ void transpose_item(const float* W, int K, int N, bf16_t* WT, LAS float* scr, int item, int lane) {
;     const int nblk = (N + 31) / 32, kb = item / nblk, nb = item % nblk, k0 = 64 * kb, n0 = 32 * nb;
;     const int nn = n0 + (lane & 31); const bool ok = nn < N;
;     float v[32];
; #pragma unroll
;     for (int i = 0; i < 32; ++i) { const int kk = 2 * i + (lane >> 5); v[i] = ok ? W[(size_t)(k0 + kk) * N + nn] : 0.f; }
; #pragma unroll
;     for (int i = 0; i < 32; ++i) { const int kk = 2 * i + (lane >> 5); scr[kk * 33 + (lane & 31)] = v[i]; }
;     LDS_WAIT(); asm volatile("" ::: "memory");
;     const int c = lane & 7;
; #pragma unroll
;     for (int j = 0; j < 4; ++j) { const int n = (lane >> 3) + 8 * j; const LAS float* s = scr + (8 * c) * 33 + n;
;         u32x4 o; o.x = pk2(s[0 * 33], s[1 * 33]); o.y = pk2(s[2 * 33], s[3 * 33]); o.z = pk2(s[4 * 33], s[5 * 33]); o.w = pk2(s[6 * 33], s[7 * 33]);
;         *(u32x4*)(WT + (size_t)(n0 + n) * K + k0 + 8 * c) = o; }
.Lp4t_la_p1_done:
	v_mad_u32_u24 v58, v0, s19, v2
	v_mad_u32_u24 v59, v0, s19, v3
	v_mad_u32_u24 v60, v0, s19, v4
	v_mad_u32_u24 v61, v0, s19, v5
	s_mov_b64 exec, s[34:35]
	s_xor_b32 m0, s6, 0x2000
	s_nop 0
	global_load_lds_dword v58, s[28:29]
	s_add_i32 m0, m0, 0x100
	s_add_u32 s28, s28, s32
	s_addc_u32 s29, s29, 0
	global_load_lds_dword v58, s[28:29]
	s_add_i32 m0, m0, 0x100
	s_add_u32 s28, s28, s32
	s_addc_u32 s29, s29, 0
	global_load_lds_dword v58, s[28:29]
	s_add_i32 m0, m0, 0x100
	s_add_u32 s28, s28, s32
	s_addc_u32 s29, s29, 0
	global_load_lds_dword v58, s[28:29]
	s_mov_b64 exec, s[34:35]
	s_add_i32 m0, m0, 0x100
	s_add_u32 s28, s28, s32
	s_addc_u32 s29, s29, 0
	global_load_lds_dword v59, s[28:29]
	s_add_i32 m0, m0, 0x100
	s_add_u32 s28, s28, s32
	s_addc_u32 s29, s29, 0
	global_load_lds_dword v59, s[28:29]
	s_add_i32 m0, m0, 0x100
	s_add_u32 s28, s28, s32
	s_addc_u32 s29, s29, 0
	global_load_lds_dword v59, s[28:29]
	s_add_i32 m0, m0, 0x100
	s_add_u32 s28, s28, s32
	s_addc_u32 s29, s29, 0
	global_load_lds_dword v59, s[28:29]
	s_mov_b64 exec, s[36:37]
	s_add_i32 m0, m0, 0x100
	s_add_u32 s28, s28, s32
	s_addc_u32 s29, s29, 0
	global_load_lds_dword v60, s[28:29]
	s_add_i32 m0, m0, 0x100
	s_add_u32 s28, s28, s32
	s_addc_u32 s29, s29, 0
	global_load_lds_dword v60, s[28:29]
	s_add_i32 m0, m0, 0x100
	s_add_u32 s28, s28, s32
	s_addc_u32 s29, s29, 0
	global_load_lds_dword v60, s[28:29]
	s_add_i32 m0, m0, 0x100
	s_add_u32 s28, s28, s32
	s_addc_u32 s29, s29, 0
	global_load_lds_dword v60, s[28:29]
	s_mov_b64 exec, s[36:37]
	s_add_i32 m0, m0, 0x100
	s_add_u32 s28, s28, s32
	s_addc_u32 s29, s29, 0
	global_load_lds_dword v61, s[28:29]
	s_add_i32 m0, m0, 0x100
	s_add_u32 s28, s28, s32
	s_addc_u32 s29, s29, 0
	global_load_lds_dword v61, s[28:29]
	s_add_i32 m0, m0, 0x100
	s_add_u32 s28, s28, s32
	s_addc_u32 s29, s29, 0
	global_load_lds_dword v61, s[28:29]
	s_add_i32 m0, m0, 0x100
	s_add_u32 s28, s28, s32
	s_addc_u32 s29, s29, 0
	global_load_lds_dword v61, s[28:29]
	s_mov_b64 exec, s[34:35]
	s_add_i32 m0, m0, 0x100
	s_add_u32 s28, s28, s32
	s_addc_u32 s29, s29, 0
	global_load_lds_dword v58, s[28:29]
	s_add_i32 m0, m0, 0x100
	s_add_u32 s28, s28, s32
	s_addc_u32 s29, s29, 0
	global_load_lds_dword v58, s[28:29]
	s_add_i32 m0, m0, 0x100
	s_add_u32 s28, s28, s32
	s_addc_u32 s29, s29, 0
	global_load_lds_dword v58, s[28:29]
	s_add_i32 m0, m0, 0x100
	s_add_u32 s28, s28, s32
	s_addc_u32 s29, s29, 0
	global_load_lds_dword v58, s[28:29]
	s_mov_b64 exec, s[34:35]
	s_add_i32 m0, m0, 0x100
	s_add_u32 s28, s28, s32
	s_addc_u32 s29, s29, 0
	global_load_lds_dword v59, s[28:29]
	s_add_i32 m0, m0, 0x100
	s_add_u32 s28, s28, s32
	s_addc_u32 s29, s29, 0
	global_load_lds_dword v59, s[28:29]
	s_add_i32 m0, m0, 0x100
	s_add_u32 s28, s28, s32
	s_addc_u32 s29, s29, 0
	global_load_lds_dword v59, s[28:29]
	s_add_i32 m0, m0, 0x100
	s_add_u32 s28, s28, s32
	s_addc_u32 s29, s29, 0
	global_load_lds_dword v59, s[28:29]
	s_mov_b64 exec, s[36:37]
	s_add_i32 m0, m0, 0x100
	s_add_u32 s28, s28, s32
	s_addc_u32 s29, s29, 0
	global_load_lds_dword v60, s[28:29]
	s_add_i32 m0, m0, 0x100
	s_add_u32 s28, s28, s32
	s_addc_u32 s29, s29, 0
	global_load_lds_dword v60, s[28:29]
	s_add_i32 m0, m0, 0x100
	s_add_u32 s28, s28, s32
	s_addc_u32 s29, s29, 0
	global_load_lds_dword v60, s[28:29]
	s_add_i32 m0, m0, 0x100
	s_add_u32 s28, s28, s32
	s_addc_u32 s29, s29, 0
	global_load_lds_dword v60, s[28:29]
	s_mov_b64 exec, s[36:37]
	s_add_i32 m0, m0, 0x100
	s_add_u32 s28, s28, s32
	s_addc_u32 s29, s29, 0
	global_load_lds_dword v61, s[28:29]
	s_add_i32 m0, m0, 0x100
	s_add_u32 s28, s28, s32
	s_addc_u32 s29, s29, 0
	global_load_lds_dword v61, s[28:29]
	s_add_i32 m0, m0, 0x100
	s_add_u32 s28, s28, s32
	s_addc_u32 s29, s29, 0
	global_load_lds_dword v61, s[28:29]
	s_add_i32 m0, m0, 0x100
	s_add_u32 s28, s28, s32
	s_addc_u32 s29, s29, 0
	global_load_lds_dword v61, s[28:29]
	s_mov_b64 exec, -1
.Lp4t_nopf1:
	s_add_i32 s5, s5, s18
.Lp4t_loop:
	s_mov_b32 s7, s4
	s_mov_b64 s[48:49], 0
	s_cmp_ge_u32 s7, 0x2020
	s_cselect_b32 s70, s99, s98
	s_add_u32 s7, s7, s70
	s_cmp_ge_u32 s7, 0x8080
	s_cbranch_scc1 .Lp4t_sa_out
	s_mul_hi_u32 s38, s7, 0x7f808
	s_mul_i32 s70, s38, 0x2020
	s_sub_u32 s7, s7, s70
	s_mul_hi_u32 s55, s7, 0xff0100
	s_mul_i32 s70, s55, 0x101
	s_sub_u32 s7, s7, s70
	s_mul_i32 s70, s38, 0x2020000
	s_cmp_eq_u32 s7, 0x100
	s_cselect_b32 s48, -1, 0
	s_mov_b32 s49, s48
	s_branch .Lp4t_sa_done
.Lp4t_sa_out:
	s_sub_u32 s7, s7, 0x8080
	s_lshr_b32 s38, s7, 11
	s_and_b32 s7, s7, 0x7ff
	s_lshr_b32 s55, s7, 6
	s_and_b32 s7, s7, 63
	s_lshl_b32 s70, s38, 23
	s_add_u32 s70, s70, 0x8200000
.Lp4t_sa_done:
	s_lshl_b32 s71, s7, 17
	s_add_u32 s70, s70, s71
	s_lshl_b32 s71, s55, 7
	s_add_u32 s70, s70, s71
	s_add_u32 s30, s26, s70
	s_addc_u32 s31, s27, 0
	s_add_i32 s70, s4, s18
	s_cmp_lt_i32 s70, s16
	s_cbranch_scc1 .Lp4t_w32
	s_waitcnt vmcnt(0)
	s_branch .Lp4t_wd

; #define LAS __attribute__((address_space(3)))
; __device__ __forceinline__ unsigned pk2(float lo, float hi) { return pg8::cvt_pk_bf16(lo, hi); }
; #define LDS_WAIT() asm volatile("s_waitcnt lgkmcnt(0)" ::: "memory")
; __device__ __forceinline__ void transpose_item(const float* W, int K, int N, bf16_t* WT, LAS float* scr, int item, int lane) {
;     ...
;     const int c = lane & 7;
; #pragma unroll
;     for (int j = 0; j < 4; ++j) { const int n = (lane >> 3) + 8 * j; const LAS float* s = scr + (8 * c) * 33 + n;
;         u32x4 o; o.x = pk2(s[0 * 33], s[1 * 33]); o.y = pk2(s[2 * 33], s[3 * 33]); o.z = pk2(s[4 * 33], s[5 * 33]); o.w = pk2(s[6 * 33], s[7 * 33]);
;         *(u32x4*)(WT + (size_t)(n0 + n) * K + k0 + 8 * c) = o; }
;     LDS_WAIT(); asm volatile("" ::: "memory");
; }
.Lp4t_wd:
	ds_read2_b32 v[18:19], v62 offset0:0 offset1:32
	ds_read2_b32 v[20:21], v62 offset0:64 offset1:96
	ds_read2_b32 v[22:23], v62 offset0:128 offset1:160
	ds_read2_b32 v[24:25], v62 offset0:192 offset1:224
	ds_read2_b32 v[26:27], v63 offset0:0 offset1:32
	ds_read2_b32 v[28:29], v63 offset0:64 offset1:96
	ds_read2_b32 v[30:31], v63 offset0:128 offset1:160
	ds_read2_b32 v[32:33], v63 offset0:192 offset1:224
	ds_read2_b32 v[34:35], v64 offset0:0 offset1:32
	ds_read2_b32 v[36:37], v64 offset0:64 offset1:96
	ds_read2_b32 v[38:39], v64 offset0:128 offset1:160
	ds_read2_b32 v[40:41], v64 offset0:192 offset1:224
	ds_read2_b32 v[42:43], v65 offset0:0 offset1:32
	ds_read2_b32 v[44:45], v65 offset0:64 offset1:96
	ds_read2_b32 v[46:47], v65 offset0:128 offset1:160
	ds_read2_b32 v[48:49], v65 offset0:192 offset1:224
	s_waitcnt lgkmcnt(12)
	v_cvt_pk_bf16_f32 v50, v18, v19
	v_cvt_pk_bf16_f32 v51, v20, v21
	v_cvt_pk_bf16_f32 v52, v22, v23
	v_cvt_pk_bf16_f32 v53, v24, v25
	global_store_dwordx4 v13, v[50:53], s[30:31]
	s_waitcnt lgkmcnt(8)
	v_cvt_pk_bf16_f32 v54, v26, v27
	v_cvt_pk_bf16_f32 v55, v28, v29
	v_cvt_pk_bf16_f32 v56, v30, v31
	v_cvt_pk_bf16_f32 v57, v32, v33
	global_store_dwordx4 v14, v[54:57], s[30:31]
	s_waitcnt lgkmcnt(4)
	v_cvt_pk_bf16_f32 v50, v34, v35
	v_cvt_pk_bf16_f32 v51, v36, v37
	v_cvt_pk_bf16_f32 v52, v38, v39
	v_cvt_pk_bf16_f32 v53, v40, v41
	v_cndmask_b32_e64 v50, v50, 0, s[48:49]
	v_cndmask_b32_e64 v51, v51, 0, s[48:49]
	v_cndmask_b32_e64 v52, v52, 0, s[48:49]
	v_cndmask_b32_e64 v53, v53, 0, s[48:49]
	global_store_dwordx4 v15, v[50:53], s[30:31]
	s_waitcnt lgkmcnt(0)
	v_cvt_pk_bf16_f32 v54, v42, v43
	v_cvt_pk_bf16_f32 v55, v44, v45
	v_cvt_pk_bf16_f32 v56, v46, v47
	v_cvt_pk_bf16_f32 v57, v48, v49
	v_cndmask_b32_e64 v54, v54, 0, s[48:49]
	v_cndmask_b32_e64 v55, v55, 0, s[48:49]
	v_cndmask_b32_e64 v56, v56, 0, s[48:49]
	v_cndmask_b32_e64 v57, v57, 0, s[48:49]
	global_store_dwordx4 v16, v[54:57], s[30:31]
	s_cmp_lt_i32 s5, s16
	s_cbranch_scc0 .Lp4t_nopf
	s_mov_b32 s7, s5
	s_cmp_ge_u32 s7, 0x2020
	s_cselect_b32 s70, s99, s98
	s_add_u32 s7, s7, s70
	s_cmp_ge_u32 s7, 0x8080
	s_cbranch_scc1 .Lp4t_la_lp_out
	s_mul_hi_u32 s38, s7, 0x7f808
	s_mul_i32 s70, s38, 0x2020
	s_sub_u32 s7, s7, s70
	s_mul_hi_u32 s55, s7, 0xff0100
	s_mul_i32 s70, s55, 0x101
	s_sub_u32 s7, s7, s70
	s_mul_i32 s70, s38, 0x4020000
	s_mul_i32 s71, s55, 0x201000
	s_add_u32 s70, s70, s71
	s_lshl_b32 s71, s7, 7
	s_add_u32 s70, s70, s71
	s_add_u32 s28, s22, s70
	s_addc_u32 s29, s23, 0
	s_mov_b32 s19, 0x8040
	s_mov_b32 s32, 0x10080
	s_mov_b64 s[34:35], -1
	s_mov_b64 s[36:37], -1
	s_cmp_eq_u32 s7, 0x100
	s_cbranch_scc0 .Lp4t_la_lp_done
	s_mov_b32 s34, 0xffff
	s_mov_b32 s35, 0xffff
	s_mov_b32 s36, 0xffff0000
	s_mov_b32 s37, 0xffff0000
	s_branch .Lp4t_la_lp_done

; #define LAS __attribute__((address_space(3)))
; __device__ __forceinline__ void transpose_item(const float* W, int K, int N, bf16_t* WT, LAS float* scr, int item, int lane) {
;     const int nblk = (N + 31) / 32, kb = item / nblk, nb = item % nblk, k0 = 64 * kb, n0 = 32 * nb;
;     const int nn = n0 + (lane & 31); const bool ok = nn < N;
;     float v[32];
; #pragma unroll
;     for (int i = 0; i < 32; ++i) { const int kk = 2 * i + (lane >> 5); v[i] = ok ? W[(size_t)(k0 + kk) * N + nn] : 0.f; }
; #pragma unroll
;     for (int i = 0; i < 32; ++i) { const int kk = 2 * i + (lane >> 5); scr[kk * 33 + (lane & 31)] = v[i]; }
.Lp4t_la_lp_done:
	v_mad_u32_u24 v58, v0, s19, v2
	v_mad_u32_u24 v59, v0, s19, v3
	v_mad_u32_u24 v60, v0, s19, v4
	v_mad_u32_u24 v61, v0, s19, v5
	s_mov_b64 exec, s[34:35]
	s_mov_b32 m0, s6
	s_nop 0
	global_load_lds_dword v58, s[28:29]
	s_add_i32 m0, m0, 0x100
	s_add_u32 s28, s28, s32
	s_addc_u32 s29, s29, 0
	global_load_lds_dword v58, s[28:29]
	s_add_i32 m0, m0, 0x100
	s_add_u32 s28, s28, s32
	s_addc_u32 s29, s29, 0
	global_load_lds_dword v58, s[28:29]
	s_add_i32 m0, m0, 0x100
	s_add_u32 s28, s28, s32
	s_addc_u32 s29, s29, 0
	global_load_lds_dword v58, s[28:29]
	s_mov_b64 exec, s[34:35]
	s_add_i32 m0, m0, 0x100
	s_add_u32 s28, s28, s32
	s_addc_u32 s29, s29, 0
	global_load_lds_dword v59, s[28:29]
	s_add_i32 m0, m0, 0x100
	s_add_u32 s28, s28, s32
	s_addc_u32 s29, s29, 0
	global_load_lds_dword v59, s[28:29]
	s_add_i32 m0, m0, 0x100
	s_add_u32 s28, s28, s32
	s_addc_u32 s29, s29, 0
	global_load_lds_dword v59, s[28:29]
	s_add_i32 m0, m0, 0x100
	s_add_u32 s28, s28, s32
	s_addc_u32 s29, s29, 0
	global_load_lds_dword v59, s[28:29]
	s_mov_b64 exec, s[36:37]
	s_add_i32 m0, m0, 0x100
	s_add_u32 s28, s28, s32
	s_addc_u32 s29, s29, 0
	global_load_lds_dword v60, s[28:29]
	s_add_i32 m0, m0, 0x100
	s_add_u32 s28, s28, s32
	s_addc_u32 s29, s29, 0
	global_load_lds_dword v60, s[28:29]
	s_add_i32 m0, m0, 0x100
	s_add_u32 s28, s28, s32
	s_addc_u32 s29, s29, 0
	global_load_lds_dword v60, s[28:29]
	s_add_i32 m0, m0, 0x100
	s_add_u32 s28, s28, s32
	s_addc_u32 s29, s29, 0
	global_load_lds_dword v60, s[28:29]
	s_mov_b64 exec, s[36:37]
	s_add_i32 m0, m0, 0x100
	s_add_u32 s28, s28, s32
	s_addc_u32 s29, s29, 0
	global_load_lds_dword v61, s[28:29]
	s_add_i32 m0, m0, 0x100
	s_add_u32 s28, s28, s32
	s_addc_u32 s29, s29, 0
	global_load_lds_dword v61, s[28:29]
	s_add_i32 m0, m0, 0x100
	s_add_u32 s28, s28, s32
	s_addc_u32 s29, s29, 0
	global_load_lds_dword v61, s[28:29]
	s_add_i32 m0, m0, 0x100
	s_add_u32 s28, s28, s32
	s_addc_u32 s29, s29, 0
	global_load_lds_dword v61, s[28:29]
	s_mov_b64 exec, s[34:35]
	s_add_i32 m0, m0, 0x100
	s_add_u32 s28, s28, s32
	s_addc_u32 s29, s29, 0
	global_load_lds_dword v58, s[28:29]
	s_add_i32 m0, m0, 0x100
	s_add_u32 s28, s28, s32
	s_addc_u32 s29, s29, 0
	global_load_lds_dword v58, s[28:29]
	s_add_i32 m0, m0, 0x100
	s_add_u32 s28, s28, s32
	s_addc_u32 s29, s29, 0
	global_load_lds_dword v58, s[28:29]
	s_add_i32 m0, m0, 0x100
	s_add_u32 s28, s28, s32
	s_addc_u32 s29, s29, 0
	global_load_lds_dword v58, s[28:29]
	s_mov_b64 exec, s[34:35]
	s_add_i32 m0, m0, 0x100
	s_add_u32 s28, s28, s32
	s_addc_u32 s29, s29, 0
	global_load_lds_dword v59, s[28:29]
	s_add_i32 m0, m0, 0x100
	s_add_u32 s28, s28, s32
	s_addc_u32 s29, s29, 0
	global_load_lds_dword v59, s[28:29]
	s_add_i32 m0, m0, 0x100
	s_add_u32 s28, s28, s32
	s_addc_u32 s29, s29, 0
	global_load_lds_dword v59, s[28:29]
	s_add_i32 m0, m0, 0x100
	s_add_u32 s28, s28, s32
	s_addc_u32 s29, s29, 0
	global_load_lds_dword v59, s[28:29]
	s_mov_b64 exec, s[36:37]
	s_add_i32 m0, m0, 0x100
	s_add_u32 s28, s28, s32
	s_addc_u32 s29, s29, 0
	global_load_lds_dword v60, s[28:29]
	s_add_i32 m0, m0, 0x100
	s_add_u32 s28, s28, s32
	s_addc_u32 s29, s29, 0
	global_load_lds_dword v60, s[28:29]
	s_add_i32 m0, m0, 0x100
	s_add_u32 s28, s28, s32
	s_addc_u32 s29, s29, 0
	global_load_lds_dword v60, s[28:29]
	s_add_i32 m0, m0, 0x100
	s_add_u32 s28, s28, s32
	s_addc_u32 s29, s29, 0
	global_load_lds_dword v60, s[28:29]
	s_mov_b64 exec, s[36:37]
	s_add_i32 m0, m0, 0x100
	s_add_u32 s28, s28, s32
	s_addc_u32 s29, s29, 0
	global_load_lds_dword v61, s[28:29]
	s_add_i32 m0, m0, 0x100
	s_add_u32 s28, s28, s32
	s_addc_u32 s29, s29, 0
	global_load_lds_dword v61, s[28:29]
	s_add_i32 m0, m0, 0x100
	s_add_u32 s28, s28, s32
	s_addc_u32 s29, s29, 0
	global_load_lds_dword v61, s[28:29]
	s_add_i32 m0, m0, 0x100
	s_add_u32 s28, s28, s32
	s_addc_u32 s29, s29, 0
	global_load_lds_dword v61, s[28:29]
	s_mov_b64 exec, -1
.Lp4t_nopf:
	s_add_i32 s5, s5, s18
	s_add_i32 s4, s4, s18
	s_xor_b32 s6, s6, 0x2000
	v_xor_b32_e32 v62, 0x2000, v62
	v_xor_b32_e32 v63, 0x2000, v63
	v_xor_b32_e32 v64, 0x2000, v64
	v_xor_b32_e32 v65, 0x2000, v65
	s_cmp_lt_i32 s4, s16
	s_cbranch_scc1 .Lp4t_loop
	s_waitcnt vmcnt(0)
.Lp4t_skip:
	s_mov_b64 s[4:5], 0
; #define LAS __attribute__((address_space(3)))
; __device__ __forceinline__ void scan_bh(LAS unsigned char* lds, const ScanP& P, int b, int h, int half, int tid, int lane, int wave) {
;     const bool cw = wave < 4;
;     const int r = lane & 15, q8 = lane >> 4, ct = half * 4 + (wave & 3), c0 = ct * 16;
;     if (!cw) {
;         const int lt = tid - 256, wrow = lt >> 4, wc16 = lt & 15, arow = lt >> 3, ac16 = lt & 7;
;         const int wperm = (wc16 >> 2) * 32 + ((((wc16 & 3) * 8) & 15) >> 2) * 8 + (((wc16 & 3) * 8) >> 4) * 4, aperm = (ac16 >> 2) * 32 + ((((ac16 & 3) * 8) & 15) >> 2) * 8 + (((ac16 & 3) * 8) >> 4) * 4;
;         const unsigned oW = (unsigned)TR_W + (unsigned)(wrow * 128 + wc16 * 8) * 2u, oQ = oW + (unsigned)(TR_Q - TR_W), oA = (unsigned)TR_A + (unsigned)(arow * 64 + ac16 * 8) * 2u, oK = oA + (unsigned)(TR_K - TR_A);
;         const unsigned lW = (unsigned)(wrow * PS + wperm) * 2u, lA = (unsigned)(arow * TS + aperm) * 2u;
;         u32x4 sa[14], sb[14];
;     ...
;         L_LOAD(0, sa); L_STORE(lds, sa); L_LOAD(1, sa);
;         __syncthreads();
.LBB0_514:
	s_and_b64 vcc, exec, s[4:5]
	s_mov_b32 s54, s13
	s_mov_b64 s[20:21], 0x28e00000
	s_cbranch_vccz .LBB0_534
	s_mov_b32 s4, -1
	s_mov_b32 s10, s2
	s_waitcnt vmcnt(0)
	v_mbcnt_lo_u32_b32 v0, s4, 0
	v_mbcnt_hi_u32_b32 v0, s4, v0
	v_or_b32_e32 v145, s3, v0
	s_mov_b64 s[4:5], s[0:1]
	s_and_b32 s8, s10, 7
	v_mov_b64_e32 v[0:1], s[4:5]
	s_waitcnt lgkmcnt(0)
	flat_load_dwordx4 v[0:3], v[0:1] offset:144
	v_readfirstlane_b32 s4, v145
	s_ashr_i32 s9, s10, 4
	s_ashr_i32 s11, s4, 6
	s_mov_b64 s[4:5], 0x22400000
	v_and_b32_e32 v144, 15, v145
	s_cmp_gt_i32 s11, 3
	s_waitcnt vmcnt(0) lgkmcnt(0)
	v_lshl_add_u64 v[116:117], v[2:3], 0, s[4:5]
	s_mov_b64 s[4:5], -1
	s_cbranch_scc0 .LBB0_525
	v_add_u32_e32 v4, 0xffffff00, v145
	v_ashrrev_i32_e32 v147, 4, v4
	v_ashrrev_i32_e32 v150, 3, v4
	v_lshlrev_b32_e32 v146, 3, v144
	v_lshlrev_b32_e32 v148, 1, v145
	v_and_b32_e32 v151, 0x60, v146
	v_lshlrev_b32_e32 v146, 4, v145
	v_and_b32_e32 v148, 4, v148
	v_lshlrev_b32_e32 v149, 3, v145
	v_and_or_b32 v146, v146, 16, v148
	v_and_b32_e32 v156, 32, v149
	v_mad_u64_u32 v[148:149], s[4:5], v147, s50, v[146:147]
	s_movk_i32 s4, 0x48
	s_nop 0
	v_mad_u64_u32 v[146:147], s[4:5], v150, s4, v[146:147]
	v_add_lshl_u32 v160, v148, v151, 1
	v_add_u32_e32 v147, 0, v160
	v_add_lshl_u32 v146, v146, v156, 1
	v_mov_b32_e32 v247, v160
	v_add_u32_e32 v248, 0xf400, v160
	v_mov_b32_e32 v249, v146
	v_add_u32_e32 v250, 0xf400, v146
	v_lshlrev_b32_e32 v5, 4, v4
	v_add_u32_e32 v240, 0x1000, v5
	v_add_u32_e32 v241, 0x3000, v5
	v_add_u32_e32 v242, 0x5000, v5
	v_add_u32_e32 v243, 0x7000, v5
	v_add_u32_e32 v244, 0x9000, v5
	v_add_u32_e32 v245, 0xb000, v5
	v_add_u32_e32 v246, 0xd000, v5
	v_readfirstlane_b32 s6, v116
	v_readfirstlane_b32 s7, v117
	s_lshl_b32 s18, s9, 8
	s_or_b32 s18, s18, s8
	s_mul_hi_u32 s15, s18, 0x1a000
	s_mul_i32 s14, s18, 0x1a000
	s_add_u32 s14, s14, s6
	s_addc_u32 s15, s15, s7
	s_mov_b32 s16, 0
	global_load_dwordx4 v[0:3], v240, s[14:15] offset:-4096
	global_load_dwordx4 v[4:7], v240, s[14:15]
	global_load_dwordx4 v[8:11], v241, s[14:15] offset:-4096
	global_load_dwordx4 v[12:15], v241, s[14:15]
	global_load_dwordx4 v[16:19], v242, s[14:15] offset:-4096
	global_load_dwordx4 v[20:23], v242, s[14:15]
	global_load_dwordx4 v[24:27], v243, s[14:15] offset:-4096
	global_load_dwordx4 v[28:31], v243, s[14:15]
	global_load_dwordx4 v[32:35], v244, s[14:15] offset:-4096
	global_load_dwordx4 v[36:39], v244, s[14:15]
	global_load_dwordx4 v[40:43], v245, s[14:15] offset:-4096
	global_load_dwordx4 v[44:47], v245, s[14:15]
	global_load_dwordx4 v[48:51], v246, s[14:15] offset:-4096
	global_load_dwordx4 v[52:55], v246, s[14:15]
	s_add_u32 s14, s14, 0xd0000
	s_addc_u32 s15, s15, 0
	global_load_dwordx4 v[56:59], v240, s[14:15] offset:-4096
	global_load_dwordx4 v[60:63], v240, s[14:15]
	global_load_dwordx4 v[64:67], v241, s[14:15] offset:-4096
	global_load_dwordx4 v[68:71], v241, s[14:15]
	global_load_dwordx4 v[72:75], v242, s[14:15] offset:-4096
	global_load_dwordx4 v[76:79], v242, s[14:15]
	global_load_dwordx4 v[80:83], v243, s[14:15] offset:-4096
	global_load_dwordx4 v[84:87], v243, s[14:15]
	global_load_dwordx4 v[88:91], v244, s[14:15] offset:-4096
	global_load_dwordx4 v[92:95], v244, s[14:15]
	global_load_dwordx4 v[96:99], v245, s[14:15] offset:-4096
	global_load_dwordx4 v[100:103], v245, s[14:15]
	global_load_dwordx4 v[104:107], v246, s[14:15] offset:-4096
	global_load_dwordx4 v[108:111], v246, s[14:15]
	s_add_u32 s14, s14, 0xd0000
	s_addc_u32 s15, s15, 0
	global_load_dwordx4 v[112:115], v240, s[14:15] offset:-4096
	global_load_dwordx4 v[116:119], v240, s[14:15]
	global_load_dwordx4 v[120:123], v241, s[14:15] offset:-4096
	global_load_dwordx4 v[124:127], v241, s[14:15]
	global_load_dwordx4 v[128:131], v242, s[14:15] offset:-4096
	global_load_dwordx4 v[132:135], v242, s[14:15]
	global_load_dwordx4 v[136:139], v243, s[14:15] offset:-4096
	global_load_dwordx4 v[140:143], v243, s[14:15]
	global_load_dwordx4 v[144:147], v244, s[14:15] offset:-4096
	global_load_dwordx4 v[148:151], v244, s[14:15]
	global_load_dwordx4 v[156:159], v245, s[14:15] offset:-4096
	global_load_dwordx4 v[160:163], v245, s[14:15]
	global_load_dwordx4 v[164:167], v246, s[14:15] offset:-4096
	global_load_dwordx4 v[168:171], v246, s[14:15]
	s_add_u32 s14, s14, 0xd0000
	s_addc_u32 s15, s15, 0
	global_load_dwordx4 v[172:175], v240, s[14:15] offset:-4096
	global_load_dwordx4 v[176:179], v240, s[14:15]
	global_load_dwordx4 v[180:183], v241, s[14:15] offset:-4096
	global_load_dwordx4 v[184:187], v241, s[14:15]
	global_load_dwordx4 v[188:191], v242, s[14:15] offset:-4096
	global_load_dwordx4 v[200:203], v242, s[14:15]
	global_load_dwordx4 v[204:207], v243, s[14:15] offset:-4096
	global_load_dwordx4 v[208:211], v243, s[14:15]
	global_load_dwordx4 v[212:215], v244, s[14:15] offset:-4096
	global_load_dwordx4 v[216:219], v244, s[14:15]
	global_load_dwordx4 v[220:223], v245, s[14:15] offset:-4096
	global_load_dwordx4 v[224:227], v245, s[14:15]
	global_load_dwordx4 v[228:231], v246, s[14:15] offset:-4096
	global_load_dwordx4 v[232:235], v246, s[14:15]
	s_add_u32 s14, s14, 0xd0000
	s_addc_u32 s15, s15, 0
	s_waitcnt vmcnt(55)
	ds_write_b64 v247, v[0:1]
	ds_write_b64 v247, v[2:3] offset:16
	s_waitcnt vmcnt(54)
	ds_write_b64 v247, v[4:5] offset:4352
	ds_write_b64 v247, v[6:7] offset:4368
	s_waitcnt vmcnt(53)
	ds_write_b64 v247, v[8:9] offset:8704
	ds_write_b64 v247, v[10:11] offset:8720
	s_waitcnt vmcnt(52)
	ds_write_b64 v247, v[12:13] offset:13056
	ds_write_b64 v247, v[14:15] offset:13072
	s_waitcnt vmcnt(51)
	ds_write_b64 v247, v[16:17] offset:17408
	ds_write_b64 v247, v[18:19] offset:17424
	s_waitcnt vmcnt(50)
	ds_write_b64 v247, v[20:21] offset:21760
	ds_write_b64 v247, v[22:23] offset:21776
	s_waitcnt vmcnt(49)
	ds_write_b64 v247, v[24:25] offset:26112
	ds_write_b64 v247, v[26:27] offset:26128
	s_waitcnt vmcnt(48)
	ds_write_b64 v247, v[28:29] offset:30464
	ds_write_b64 v247, v[30:31] offset:30480
	s_waitcnt vmcnt(47)
	ds_write_b64 v249, v[32:33] offset:34816
	ds_write_b64 v249, v[34:35] offset:34832
	s_waitcnt vmcnt(46)
	ds_write_b64 v249, v[36:37] offset:39424
	ds_write_b64 v249, v[38:39] offset:39440
	s_waitcnt vmcnt(45)
	ds_write_b64 v249, v[40:41] offset:44032
	ds_write_b64 v249, v[42:43] offset:44048
	s_waitcnt vmcnt(44)
	ds_write_b64 v249, v[44:45] offset:48640
	ds_write_b64 v249, v[46:47] offset:48656
	s_waitcnt vmcnt(43)
	ds_write_b64 v249, v[48:49] offset:53248
	ds_write_b64 v249, v[50:51] offset:53264
	s_waitcnt vmcnt(42)
	ds_write_b64 v249, v[52:53] offset:57856
	ds_write_b64 v249, v[54:55] offset:57872
	s_waitcnt lgkmcnt(0)
	s_barrier
